# GEMM K-loops: s_setprio 1 / s_setprio 0 moved outside the barrier-delimited MFMA blocks (raised before the opening barrier, lowered after the closing barrier), so each block is 32 bare MFMAs
# speedup vs baseline: 1.0109x; 1.0003x over previous
.LBB0_50:
	s_add_u32 s8, s58, 0xfffc0080
	s_addc_u32 s9, s59, -1
	s_add_i32 s10, 0, 0x10000
	s_cmp_eq_u32 s85, 12
	s_cselect_b32 s41, s53, s9
	s_cselect_b32 s40, s69, s8
	s_cselect_b32 s29, s51, s84
	s_cselect_b32 s28, s72, s73
	s_add_i32 s11, 0, 0x14000
	v_add_u32_e32 v158, s10, v150
	v_add_u32_e32 v174, s11, v150
	ds_read_b128 v[142:145], v158
	ds_read_b128 v[146:149], v158 offset:1024
	ds_read_b128 v[154:157], v158 offset:2048
	ds_read_b128 v[158:161], v158 offset:3072
	ds_read_b128 v[162:165], v174
	ds_read_b128 v[166:169], v174 offset:1024
	ds_read_b128 v[170:173], v174 offset:2048
	ds_read_b128 v[174:177], v174 offset:3072
	v_lshl_add_u64 v[210:211], s[58:59], 0, v[138:139]
	s_add_i32 m0, s61, 0xc000
	ds_read_b128 v[178:181], v153
	ds_read_b128 v[182:185], v153 offset:1024
	ds_read_b128 v[186:189], v153 offset:2048
	ds_read_b128 v[190:193], v153 offset:3072
	ds_read_b128 v[194:197], v153 offset:4096
	ds_read_b128 v[198:201], v153 offset:5120
	ds_read_b128 v[202:205], v153 offset:6144
	ds_read_b128 v[206:209], v153 offset:7168
	global_load_lds_dwordx4 v[210:211], off
	v_lshl_add_u64 v[210:211], s[58:59], 0, v[140:141]
	s_add_i32 m0, s61, 0xe000
	s_nop 0
	global_load_lds_dwordx4 v[210:211], off
	s_waitcnt vmcnt(8)
	s_waitcnt lgkmcnt(0)
	s_setprio 1
	s_barrier
	v_mfma_f32_16x16x32_bf16 v[126:129], v[142:145], v[178:181], v[126:129]
	v_mfma_f32_16x16x32_bf16 v[118:121], v[154:157], v[178:181], v[118:121]
	v_mfma_f32_16x16x32_bf16 v[110:113], v[142:145], v[186:189], v[110:113]
	v_mfma_f32_16x16x32_bf16 v[102:105], v[154:157], v[186:189], v[102:105]
	v_mfma_f32_16x16x32_bf16 v[94:97], v[142:145], v[194:197], v[94:97]
	v_mfma_f32_16x16x32_bf16 v[86:89], v[154:157], v[194:197], v[86:89]
	v_mfma_f32_16x16x32_bf16 v[78:81], v[142:145], v[202:205], v[78:81]
	v_mfma_f32_16x16x32_bf16 v[70:73], v[154:157], v[202:205], v[70:73]
	v_mfma_f32_16x16x32_bf16 v[126:129], v[146:149], v[182:185], v[126:129]
	v_mfma_f32_16x16x32_bf16 v[118:121], v[158:161], v[182:185], v[118:121]
	v_mfma_f32_16x16x32_bf16 v[110:113], v[146:149], v[190:193], v[110:113]
	v_mfma_f32_16x16x32_bf16 v[102:105], v[158:161], v[190:193], v[102:105]
	v_mfma_f32_16x16x32_bf16 v[94:97], v[146:149], v[198:201], v[94:97]
	v_mfma_f32_16x16x32_bf16 v[86:89], v[158:161], v[198:201], v[86:89]
	v_mfma_f32_16x16x32_bf16 v[78:81], v[146:149], v[206:209], v[78:81]
	v_mfma_f32_16x16x32_bf16 v[70:73], v[158:161], v[206:209], v[70:73]
	v_mfma_f32_16x16x32_bf16 v[122:125], v[162:165], v[178:181], v[122:125]
	v_mfma_f32_16x16x32_bf16 v[114:117], v[170:173], v[178:181], v[114:117]
	v_mfma_f32_16x16x32_bf16 v[106:109], v[162:165], v[186:189], v[106:109]
	v_mfma_f32_16x16x32_bf16 v[98:101], v[170:173], v[186:189], v[98:101]
	v_mfma_f32_16x16x32_bf16 v[90:93], v[162:165], v[194:197], v[90:93]
	v_mfma_f32_16x16x32_bf16 v[82:85], v[170:173], v[194:197], v[82:85]
	v_mfma_f32_16x16x32_bf16 v[74:77], v[162:165], v[202:205], v[74:77]
	v_mfma_f32_16x16x32_bf16 v[66:69], v[170:173], v[202:205], v[66:69]
	v_mfma_f32_16x16x32_bf16 v[122:125], v[166:169], v[182:185], v[122:125]
	v_mfma_f32_16x16x32_bf16 v[114:117], v[174:177], v[182:185], v[114:117]
	v_mfma_f32_16x16x32_bf16 v[106:109], v[166:169], v[190:193], v[106:109]
	v_mfma_f32_16x16x32_bf16 v[98:101], v[174:177], v[190:193], v[98:101]
	v_mfma_f32_16x16x32_bf16 v[90:93], v[166:169], v[198:201], v[90:93]
	v_mfma_f32_16x16x32_bf16 v[82:85], v[174:177], v[198:201], v[82:85]
	v_mfma_f32_16x16x32_bf16 v[74:77], v[166:169], v[206:209], v[74:77]
	v_mfma_f32_16x16x32_bf16 v[66:69], v[174:177], v[206:209], v[66:69]
	s_barrier
	s_setprio 0
	s_add_i32 s8, s10, s31
	v_lshl_add_u64 v[210:211], s[28:29], 0, v[130:131]
	s_mov_b32 m0, s8
	ds_read_b128 v[178:181], v153 offset:16384
	ds_read_b128 v[182:185], v153 offset:17408
	ds_read_b128 v[186:189], v153 offset:18432
	ds_read_b128 v[190:193], v153 offset:19456
	ds_read_b128 v[194:197], v153 offset:20480
	ds_read_b128 v[198:201], v153 offset:21504
	ds_read_b128 v[202:205], v153 offset:22528
	ds_read_b128 v[206:209], v153 offset:23552
	global_load_lds_dwordx4 v[210:211], off
	s_add_i32 m0, s8, 0x2000
	s_add_u32 s8, s28, 0x40000
	v_lshl_add_u64 v[212:213], s[28:29], 0, v[132:133]
	s_addc_u32 s9, s29, 0
	s_add_i32 s10, s11, s31
	global_load_lds_dwordx4 v[212:213], off
	v_lshl_add_u64 v[214:215], s[8:9], 0, v[130:131]
	s_mov_b32 m0, s10
	v_lshl_add_u64 v[216:217], s[40:41], 0, v[134:135]
	global_load_lds_dwordx4 v[214:215], off
	v_lshl_add_u64 v[214:215], s[8:9], 0, v[132:133]
	s_add_i32 m0, s10, 0x2000
	s_nop 0
	global_load_lds_dwordx4 v[214:215], off
	v_lshl_add_u64 v[214:215], s[40:41], 0, v[136:137]
	s_mov_b32 m0, s61
	s_nop 0
	global_load_lds_dwordx4 v[214:215], off
	s_mov_b32 m0, s62
	s_nop 0
	global_load_lds_dwordx4 v[216:217], off
	s_waitcnt vmcnt(8)
	s_waitcnt lgkmcnt(0)
	s_setprio 1
	s_barrier
	v_mfma_f32_16x16x32_bf16 v[62:65], v[142:145], v[178:181], v[62:65]
	v_mfma_f32_16x16x32_bf16 v[54:57], v[154:157], v[178:181], v[54:57]
	v_mfma_f32_16x16x32_bf16 v[46:49], v[142:145], v[186:189], v[46:49]
	v_mfma_f32_16x16x32_bf16 v[38:41], v[154:157], v[186:189], v[38:41]
	v_mfma_f32_16x16x32_bf16 v[30:33], v[142:145], v[194:197], v[30:33]
	v_mfma_f32_16x16x32_bf16 v[22:25], v[154:157], v[194:197], v[22:25]
	v_mfma_f32_16x16x32_bf16 v[14:17], v[142:145], v[202:205], v[14:17]
	v_mfma_f32_16x16x32_bf16 v[6:9], v[154:157], v[202:205], v[6:9]
	v_mfma_f32_16x16x32_bf16 v[62:65], v[146:149], v[182:185], v[62:65]
	v_mfma_f32_16x16x32_bf16 v[54:57], v[158:161], v[182:185], v[54:57]
	v_mfma_f32_16x16x32_bf16 v[46:49], v[146:149], v[190:193], v[46:49]
	v_mfma_f32_16x16x32_bf16 v[38:41], v[158:161], v[190:193], v[38:41]
	v_mfma_f32_16x16x32_bf16 v[30:33], v[146:149], v[198:201], v[30:33]
	v_mfma_f32_16x16x32_bf16 v[22:25], v[158:161], v[198:201], v[22:25]
	v_mfma_f32_16x16x32_bf16 v[14:17], v[146:149], v[206:209], v[14:17]
	v_mfma_f32_16x16x32_bf16 v[6:9], v[158:161], v[206:209], v[6:9]
	v_mfma_f32_16x16x32_bf16 v[58:61], v[162:165], v[178:181], v[58:61]
	v_mfma_f32_16x16x32_bf16 v[50:53], v[170:173], v[178:181], v[50:53]
	v_mfma_f32_16x16x32_bf16 v[42:45], v[162:165], v[186:189], v[42:45]
	v_mfma_f32_16x16x32_bf16 v[34:37], v[170:173], v[186:189], v[34:37]
	v_mfma_f32_16x16x32_bf16 v[26:29], v[162:165], v[194:197], v[26:29]
	v_mfma_f32_16x16x32_bf16 v[18:21], v[170:173], v[194:197], v[18:21]
	v_mfma_f32_16x16x32_bf16 v[10:13], v[162:165], v[202:205], v[10:13]
	v_mfma_f32_16x16x32_bf16 v[2:5], v[170:173], v[202:205], v[2:5]
	v_mfma_f32_16x16x32_bf16 v[58:61], v[166:169], v[182:185], v[58:61]
	v_mfma_f32_16x16x32_bf16 v[50:53], v[174:177], v[182:185], v[50:53]
	v_mfma_f32_16x16x32_bf16 v[42:45], v[166:169], v[190:193], v[42:45]
	v_mfma_f32_16x16x32_bf16 v[34:37], v[174:177], v[190:193], v[34:37]
	v_mfma_f32_16x16x32_bf16 v[26:29], v[166:169], v[198:201], v[26:29]
	v_mfma_f32_16x16x32_bf16 v[18:21], v[174:177], v[198:201], v[18:21]
	v_mfma_f32_16x16x32_bf16 v[10:13], v[166:169], v[206:209], v[10:13]
	v_mfma_f32_16x16x32_bf16 v[2:5], v[174:177], v[206:209], v[2:5]
	s_barrier
	s_setprio 0
	s_add_i32 s10, 0, 0x18000
	s_add_i32 s11, 0, 0x1c000
	v_add_u32_e32 v158, s10, v150
	v_add_u32_e32 v174, s11, v150
	ds_read_b128 v[142:145], v158
	ds_read_b128 v[146:149], v158 offset:1024
	ds_read_b128 v[154:157], v158 offset:2048
	ds_read_b128 v[158:161], v158 offset:3072
	ds_read_b128 v[162:165], v174
	ds_read_b128 v[166:169], v174 offset:1024
	ds_read_b128 v[170:173], v174 offset:2048
	ds_read_b128 v[174:177], v174 offset:3072
	s_add_u32 s8, s40, 0x40000
	s_addc_u32 s9, s41, 0
	s_mov_b32 m0, s63
	v_lshl_add_u64 v[218:219], s[8:9], 0, v[136:137]
	ds_read_b128 v[178:181], v153 offset:32768
	ds_read_b128 v[182:185], v153 offset:33792
	ds_read_b128 v[186:189], v153 offset:34816
	ds_read_b128 v[190:193], v153 offset:35840
	ds_read_b128 v[194:197], v153 offset:36864
	ds_read_b128 v[198:201], v153 offset:37888
	ds_read_b128 v[202:205], v153 offset:38912
	ds_read_b128 v[206:209], v153 offset:39936
	global_load_lds_dwordx4 v[218:219], off
	v_lshl_add_u64 v[218:219], s[8:9], 0, v[134:135]
	s_mov_b32 m0, s64
	s_nop 0
	global_load_lds_dwordx4 v[218:219], off
	s_waitcnt vmcnt(8)
	s_waitcnt lgkmcnt(0)
	s_setprio 1
	s_barrier
	v_mfma_f32_16x16x32_bf16 v[126:129], v[142:145], v[178:181], v[126:129]
	v_mfma_f32_16x16x32_bf16 v[118:121], v[154:157], v[178:181], v[118:121]
	v_mfma_f32_16x16x32_bf16 v[110:113], v[142:145], v[186:189], v[110:113]
	v_mfma_f32_16x16x32_bf16 v[102:105], v[154:157], v[186:189], v[102:105]
	v_mfma_f32_16x16x32_bf16 v[94:97], v[142:145], v[194:197], v[94:97]
	v_mfma_f32_16x16x32_bf16 v[86:89], v[154:157], v[194:197], v[86:89]
	v_mfma_f32_16x16x32_bf16 v[78:81], v[142:145], v[202:205], v[78:81]
	v_mfma_f32_16x16x32_bf16 v[70:73], v[154:157], v[202:205], v[70:73]
	v_mfma_f32_16x16x32_bf16 v[126:129], v[146:149], v[182:185], v[126:129]
	v_mfma_f32_16x16x32_bf16 v[118:121], v[158:161], v[182:185], v[118:121]
	v_mfma_f32_16x16x32_bf16 v[110:113], v[146:149], v[190:193], v[110:113]
	v_mfma_f32_16x16x32_bf16 v[102:105], v[158:161], v[190:193], v[102:105]
	v_mfma_f32_16x16x32_bf16 v[94:97], v[146:149], v[198:201], v[94:97]
	v_mfma_f32_16x16x32_bf16 v[86:89], v[158:161], v[198:201], v[86:89]
	v_mfma_f32_16x16x32_bf16 v[78:81], v[146:149], v[206:209], v[78:81]
	v_mfma_f32_16x16x32_bf16 v[70:73], v[158:161], v[206:209], v[70:73]
	v_mfma_f32_16x16x32_bf16 v[122:125], v[162:165], v[178:181], v[122:125]
	v_mfma_f32_16x16x32_bf16 v[114:117], v[170:173], v[178:181], v[114:117]
	v_mfma_f32_16x16x32_bf16 v[106:109], v[162:165], v[186:189], v[106:109]
	v_mfma_f32_16x16x32_bf16 v[98:101], v[170:173], v[186:189], v[98:101]
	v_mfma_f32_16x16x32_bf16 v[90:93], v[162:165], v[194:197], v[90:93]
	v_mfma_f32_16x16x32_bf16 v[82:85], v[170:173], v[194:197], v[82:85]
	v_mfma_f32_16x16x32_bf16 v[74:77], v[162:165], v[202:205], v[74:77]
	v_mfma_f32_16x16x32_bf16 v[66:69], v[170:173], v[202:205], v[66:69]
	v_mfma_f32_16x16x32_bf16 v[122:125], v[166:169], v[182:185], v[122:125]
	v_mfma_f32_16x16x32_bf16 v[114:117], v[174:177], v[182:185], v[114:117]
	v_mfma_f32_16x16x32_bf16 v[106:109], v[166:169], v[190:193], v[106:109]
	v_mfma_f32_16x16x32_bf16 v[98:101], v[174:177], v[190:193], v[98:101]
	v_mfma_f32_16x16x32_bf16 v[90:93], v[166:169], v[198:201], v[90:93]
	v_mfma_f32_16x16x32_bf16 v[82:85], v[174:177], v[198:201], v[82:85]
	v_mfma_f32_16x16x32_bf16 v[74:77], v[166:169], v[206:209], v[74:77]
	v_mfma_f32_16x16x32_bf16 v[66:69], v[174:177], v[206:209], v[66:69]
	s_barrier
	s_setprio 0
	s_add_i32 s8, s10, s31
	v_lshl_add_u64 v[210:211], v[210:211], 0, s[82:83]
	s_mov_b32 m0, s8
	ds_read_b128 v[178:181], v153 offset:49152
	ds_read_b128 v[182:185], v153 offset:50176
	ds_read_b128 v[186:189], v153 offset:51200
	ds_read_b128 v[190:193], v153 offset:52224
	ds_read_b128 v[194:197], v153 offset:53248
	ds_read_b128 v[198:201], v153 offset:54272
	ds_read_b128 v[202:205], v153 offset:55296
	ds_read_b128 v[206:209], v153 offset:56320
	global_load_lds_dwordx4 v[210:211], off
	s_add_i32 m0, s8, 0x2000
	s_add_u32 s8, s28, 0x40080
	v_lshl_add_u64 v[210:211], v[212:213], 0, s[82:83]
	s_addc_u32 s9, s29, 0
	s_add_i32 s10, s11, s31
	global_load_lds_dwordx4 v[210:211], off
	v_lshl_add_u64 v[210:211], s[8:9], 0, v[130:131]
	s_mov_b32 m0, s10
	s_nop 0
	global_load_lds_dwordx4 v[210:211], off
	v_lshl_add_u64 v[210:211], s[8:9], 0, v[132:133]
	s_add_i32 m0, s10, 0x2000
	s_nop 0
	global_load_lds_dwordx4 v[210:211], off
	v_lshl_add_u64 v[210:211], v[214:215], 0, s[82:83]
	s_mov_b32 m0, s65
	s_nop 0
	global_load_lds_dwordx4 v[210:211], off
	v_lshl_add_u64 v[210:211], v[216:217], 0, s[82:83]
	s_mov_b32 m0, s66
	s_nop 0
	global_load_lds_dwordx4 v[210:211], off
	s_waitcnt vmcnt(8)
	s_waitcnt lgkmcnt(0)
	s_setprio 1
	s_barrier
	v_mfma_f32_16x16x32_bf16 v[62:65], v[142:145], v[178:181], v[62:65]
	v_mfma_f32_16x16x32_bf16 v[54:57], v[154:157], v[178:181], v[54:57]
	v_mfma_f32_16x16x32_bf16 v[46:49], v[142:145], v[186:189], v[46:49]
	v_mfma_f32_16x16x32_bf16 v[38:41], v[154:157], v[186:189], v[38:41]
	v_mfma_f32_16x16x32_bf16 v[30:33], v[142:145], v[194:197], v[30:33]
	v_mfma_f32_16x16x32_bf16 v[22:25], v[154:157], v[194:197], v[22:25]
	v_mfma_f32_16x16x32_bf16 v[14:17], v[142:145], v[202:205], v[14:17]
	v_mfma_f32_16x16x32_bf16 v[6:9], v[154:157], v[202:205], v[6:9]
	v_mfma_f32_16x16x32_bf16 v[62:65], v[146:149], v[182:185], v[62:65]
	v_mfma_f32_16x16x32_bf16 v[54:57], v[158:161], v[182:185], v[54:57]
	v_mfma_f32_16x16x32_bf16 v[46:49], v[146:149], v[190:193], v[46:49]
	v_mfma_f32_16x16x32_bf16 v[38:41], v[158:161], v[190:193], v[38:41]
	v_mfma_f32_16x16x32_bf16 v[30:33], v[146:149], v[198:201], v[30:33]
	v_mfma_f32_16x16x32_bf16 v[22:25], v[158:161], v[198:201], v[22:25]
	v_mfma_f32_16x16x32_bf16 v[14:17], v[146:149], v[206:209], v[14:17]
	v_mfma_f32_16x16x32_bf16 v[6:9], v[158:161], v[206:209], v[6:9]
	v_mfma_f32_16x16x32_bf16 v[58:61], v[162:165], v[178:181], v[58:61]
	v_mfma_f32_16x16x32_bf16 v[50:53], v[170:173], v[178:181], v[50:53]
	v_mfma_f32_16x16x32_bf16 v[42:45], v[162:165], v[186:189], v[42:45]
	v_mfma_f32_16x16x32_bf16 v[34:37], v[170:173], v[186:189], v[34:37]
	v_mfma_f32_16x16x32_bf16 v[26:29], v[162:165], v[194:197], v[26:29]
	v_mfma_f32_16x16x32_bf16 v[18:21], v[170:173], v[194:197], v[18:21]
	v_mfma_f32_16x16x32_bf16 v[10:13], v[162:165], v[202:205], v[10:13]
	v_mfma_f32_16x16x32_bf16 v[2:5], v[170:173], v[202:205], v[2:5]
	v_mfma_f32_16x16x32_bf16 v[58:61], v[166:169], v[182:185], v[58:61]
	v_mfma_f32_16x16x32_bf16 v[50:53], v[174:177], v[182:185], v[50:53]
	v_mfma_f32_16x16x32_bf16 v[42:45], v[166:169], v[190:193], v[42:45]
	v_mfma_f32_16x16x32_bf16 v[34:37], v[174:177], v[190:193], v[34:37]
	v_mfma_f32_16x16x32_bf16 v[26:29], v[166:169], v[198:201], v[26:29]
	v_mfma_f32_16x16x32_bf16 v[18:21], v[174:177], v[198:201], v[18:21]
	v_mfma_f32_16x16x32_bf16 v[10:13], v[166:169], v[206:209], v[10:13]
	v_mfma_f32_16x16x32_bf16 v[2:5], v[174:177], v[206:209], v[2:5]
	s_barrier
	s_setprio 0
	s_add_i32 s85, s85, 2
	s_add_u32 s58, s58, 0x100
	s_addc_u32 s59, s59, 0
	s_add_u32 s73, s73, 0x100
	s_addc_u32 s84, s84, 0
	s_cmp_gt_u32 s85, 13
	s_cbranch_scc0 .LBB0_50
	s_and_b64 vcc, exec, s[48:49]
	s_cbranch_vccz .LBB0_53
	s_barrier

.LBB0_75:
	s_add_i32 s41, s28, 2
	s_add_u32 s8, s60, 0x80
	s_addc_u32 s9, s61, 0
	s_add_i32 s10, 0, 0x10000
	s_cmp_eq_u32 s84, s28
	s_cselect_b32 s29, s47, s9
	s_cselect_b32 s28, s46, s8
	s_cselect_b32 s9, s59, s40
	s_cselect_b32 s8, s58, s7
	s_add_i32 s11, 0, 0x14000
	v_add_u32_e32 v126, s10, v1
	v_add_u32_e32 v160, s11, v1
	ds_read_b128 v[98:101], v126
	ds_read_b128 v[102:105], v126 offset:1024
	ds_read_b128 v[122:125], v126 offset:2048
	ds_read_b128 v[126:129], v126 offset:3072
	ds_read_b128 v[144:147], v160
	ds_read_b128 v[148:151], v160 offset:1024
	ds_read_b128 v[156:159], v160 offset:2048
	ds_read_b128 v[160:163], v160 offset:3072
	v_lshl_add_u64 v[206:207], s[60:61], 0, v[194:195]
	s_add_i32 m0, s66, 0xc000
	ds_read_b128 v[164:167], v231
	ds_read_b128 v[168:171], v231 offset:1024
	ds_read_b128 v[172:175], v231 offset:2048
	ds_read_b128 v[176:179], v231 offset:3072
	ds_read_b128 v[180:183], v231 offset:4096
	ds_read_b128 v[184:187], v231 offset:5120
	ds_read_b128 v[198:201], v231 offset:6144
	ds_read_b128 v[202:205], v231 offset:7168
	global_load_lds_dwordx4 v[206:207], off
	v_lshl_add_u64 v[206:207], s[60:61], 0, v[196:197]
	s_add_i32 m0, s66, 0xe000
	s_nop 0
	global_load_lds_dwordx4 v[206:207], off
	s_waitcnt vmcnt(8)
	s_waitcnt lgkmcnt(0)
	s_setprio 1
	s_barrier
	v_mfma_f32_16x16x32_bf16 v[152:155], v[98:101], v[164:167], v[152:155]
	v_mfma_f32_16x16x32_bf16 v[140:143], v[122:125], v[164:167], v[140:143]
	v_mfma_f32_16x16x32_bf16 v[118:121], v[98:101], v[172:175], v[118:121]
	v_mfma_f32_16x16x32_bf16 v[114:117], v[122:125], v[172:175], v[114:117]
	v_mfma_f32_16x16x32_bf16 v[94:97], v[98:101], v[180:183], v[94:97]
	v_mfma_f32_16x16x32_bf16 v[90:93], v[122:125], v[180:183], v[90:93]
	v_mfma_f32_16x16x32_bf16 v[78:81], v[98:101], v[198:201], v[78:81]
	v_mfma_f32_16x16x32_bf16 v[74:77], v[122:125], v[198:201], v[74:77]
	v_mfma_f32_16x16x32_bf16 v[152:155], v[102:105], v[168:171], v[152:155]
	v_mfma_f32_16x16x32_bf16 v[140:143], v[126:129], v[168:171], v[140:143]
	v_mfma_f32_16x16x32_bf16 v[118:121], v[102:105], v[176:179], v[118:121]
	v_mfma_f32_16x16x32_bf16 v[114:117], v[126:129], v[176:179], v[114:117]
	v_mfma_f32_16x16x32_bf16 v[94:97], v[102:105], v[184:187], v[94:97]
	v_mfma_f32_16x16x32_bf16 v[90:93], v[126:129], v[184:187], v[90:93]
	v_mfma_f32_16x16x32_bf16 v[78:81], v[102:105], v[202:205], v[78:81]
	v_mfma_f32_16x16x32_bf16 v[74:77], v[126:129], v[202:205], v[74:77]
	v_mfma_f32_16x16x32_bf16 v[136:139], v[144:147], v[164:167], v[136:139]
	v_mfma_f32_16x16x32_bf16 v[132:135], v[156:159], v[164:167], v[132:135]
	v_mfma_f32_16x16x32_bf16 v[110:113], v[144:147], v[172:175], v[110:113]
	v_mfma_f32_16x16x32_bf16 v[106:109], v[156:159], v[172:175], v[106:109]
	v_mfma_f32_16x16x32_bf16 v[86:89], v[144:147], v[180:183], v[86:89]
	v_mfma_f32_16x16x32_bf16 v[82:85], v[156:159], v[180:183], v[82:85]
	v_mfma_f32_16x16x32_bf16 v[70:73], v[144:147], v[198:201], v[70:73]
	v_mfma_f32_16x16x32_bf16 v[66:69], v[156:159], v[198:201], v[66:69]
	v_mfma_f32_16x16x32_bf16 v[136:139], v[148:151], v[168:171], v[136:139]
	v_mfma_f32_16x16x32_bf16 v[132:135], v[160:163], v[168:171], v[132:135]
	v_mfma_f32_16x16x32_bf16 v[110:113], v[148:151], v[176:179], v[110:113]
	v_mfma_f32_16x16x32_bf16 v[106:109], v[160:163], v[176:179], v[106:109]
	v_mfma_f32_16x16x32_bf16 v[86:89], v[148:151], v[184:187], v[86:89]
	v_mfma_f32_16x16x32_bf16 v[82:85], v[160:163], v[184:187], v[82:85]
	v_mfma_f32_16x16x32_bf16 v[70:73], v[148:151], v[202:205], v[70:73]
	v_mfma_f32_16x16x32_bf16 v[66:69], v[160:163], v[202:205], v[66:69]
	s_barrier
	s_setprio 0
	s_add_i32 s10, s10, s64
	v_lshl_add_u64 v[206:207], s[8:9], 0, v[130:131]
	s_mov_b32 m0, s10
	ds_read_b128 v[164:167], v231 offset:16384
	ds_read_b128 v[168:171], v231 offset:17408
	ds_read_b128 v[172:175], v231 offset:18432
	ds_read_b128 v[176:179], v231 offset:19456
	ds_read_b128 v[180:183], v231 offset:20480
	ds_read_b128 v[184:187], v231 offset:21504
	ds_read_b128 v[198:201], v231 offset:22528
	ds_read_b128 v[202:205], v231 offset:23552
	global_load_lds_dwordx4 v[206:207], off
	s_add_i32 m0, s10, 0x2000
	v_lshl_add_u64 v[208:209], s[8:9], 0, v[188:189]
	s_add_u32 s8, s8, s48
	s_addc_u32 s9, s9, 0
	s_add_i32 s10, s11, s64
	global_load_lds_dwordx4 v[208:209], off
	v_lshl_add_u64 v[210:211], s[8:9], 0, v[130:131]
	s_mov_b32 m0, s10
	v_lshl_add_u64 v[212:213], s[8:9], 0, v[188:189]
	global_load_lds_dwordx4 v[210:211], off
	s_add_i32 m0, s10, 0x2000
	v_lshl_add_u64 v[214:215], s[28:29], 0, v[192:193]
	global_load_lds_dwordx4 v[212:213], off
	s_mov_b32 m0, s66
	v_lshl_add_u64 v[216:217], s[28:29], 0, v[190:191]
	global_load_lds_dwordx4 v[214:215], off
	s_mov_b32 m0, s67
	s_nop 0
	global_load_lds_dwordx4 v[216:217], off
	s_waitcnt vmcnt(8)
	s_waitcnt lgkmcnt(0)
	s_setprio 1
	s_barrier
	v_mfma_f32_16x16x32_bf16 v[62:65], v[98:101], v[164:167], v[62:65]
	v_mfma_f32_16x16x32_bf16 v[58:61], v[122:125], v[164:167], v[58:61]
	v_mfma_f32_16x16x32_bf16 v[46:49], v[98:101], v[172:175], v[46:49]
	v_mfma_f32_16x16x32_bf16 v[42:45], v[122:125], v[172:175], v[42:45]
	v_mfma_f32_16x16x32_bf16 v[30:33], v[98:101], v[180:183], v[30:33]
	v_mfma_f32_16x16x32_bf16 v[26:29], v[122:125], v[180:183], v[26:29]
	v_mfma_f32_16x16x32_bf16 v[14:17], v[98:101], v[198:201], v[14:17]
	v_mfma_f32_16x16x32_bf16 v[10:13], v[122:125], v[198:201], v[10:13]
	v_mfma_f32_16x16x32_bf16 v[62:65], v[102:105], v[168:171], v[62:65]
	v_mfma_f32_16x16x32_bf16 v[58:61], v[126:129], v[168:171], v[58:61]
	v_mfma_f32_16x16x32_bf16 v[46:49], v[102:105], v[176:179], v[46:49]
	v_mfma_f32_16x16x32_bf16 v[42:45], v[126:129], v[176:179], v[42:45]
	v_mfma_f32_16x16x32_bf16 v[30:33], v[102:105], v[184:187], v[30:33]
	v_mfma_f32_16x16x32_bf16 v[26:29], v[126:129], v[184:187], v[26:29]
	v_mfma_f32_16x16x32_bf16 v[14:17], v[102:105], v[202:205], v[14:17]
	v_mfma_f32_16x16x32_bf16 v[10:13], v[126:129], v[202:205], v[10:13]
	v_mfma_f32_16x16x32_bf16 v[54:57], v[144:147], v[164:167], v[54:57]
	v_mfma_f32_16x16x32_bf16 v[50:53], v[156:159], v[164:167], v[50:53]
	v_mfma_f32_16x16x32_bf16 v[38:41], v[144:147], v[172:175], v[38:41]
	v_mfma_f32_16x16x32_bf16 v[34:37], v[156:159], v[172:175], v[34:37]
	v_mfma_f32_16x16x32_bf16 v[22:25], v[144:147], v[180:183], v[22:25]
	v_mfma_f32_16x16x32_bf16 v[18:21], v[156:159], v[180:183], v[18:21]
	v_mfma_f32_16x16x32_bf16 v[6:9], v[144:147], v[198:201], v[6:9]
	v_mfma_f32_16x16x32_bf16 v[2:5], v[156:159], v[198:201], v[2:5]
	v_mfma_f32_16x16x32_bf16 v[54:57], v[148:151], v[168:171], v[54:57]
	v_mfma_f32_16x16x32_bf16 v[50:53], v[160:163], v[168:171], v[50:53]
	v_mfma_f32_16x16x32_bf16 v[38:41], v[148:151], v[176:179], v[38:41]
	v_mfma_f32_16x16x32_bf16 v[34:37], v[160:163], v[176:179], v[34:37]
	v_mfma_f32_16x16x32_bf16 v[22:25], v[148:151], v[184:187], v[22:25]
	v_mfma_f32_16x16x32_bf16 v[18:21], v[160:163], v[184:187], v[18:21]
	v_mfma_f32_16x16x32_bf16 v[6:9], v[148:151], v[202:205], v[6:9]
	v_mfma_f32_16x16x32_bf16 v[2:5], v[160:163], v[202:205], v[2:5]
	s_barrier
	s_setprio 0
	s_add_i32 s10, 0, 0x18000
	s_add_i32 s11, 0, 0x1c000
	v_add_u32_e32 v126, s10, v1
	v_add_u32_e32 v160, s11, v1
	ds_read_b128 v[98:101], v126
	ds_read_b128 v[102:105], v126 offset:1024
	ds_read_b128 v[122:125], v126 offset:2048
	ds_read_b128 v[126:129], v126 offset:3072
	ds_read_b128 v[144:147], v160
	ds_read_b128 v[148:151], v160 offset:1024
	ds_read_b128 v[156:159], v160 offset:2048
	ds_read_b128 v[160:163], v160 offset:3072
	s_add_u32 s8, s28, s48
	s_addc_u32 s9, s29, 0
	s_mov_b32 m0, s68
	v_lshl_add_u64 v[218:219], s[8:9], 0, v[192:193]
	ds_read_b128 v[164:167], v231 offset:32768
	ds_read_b128 v[168:171], v231 offset:33792
	ds_read_b128 v[172:175], v231 offset:34816
	ds_read_b128 v[176:179], v231 offset:35840
	ds_read_b128 v[180:183], v231 offset:36864
	ds_read_b128 v[184:187], v231 offset:37888
	ds_read_b128 v[198:201], v231 offset:38912
	ds_read_b128 v[202:205], v231 offset:39936
	global_load_lds_dwordx4 v[218:219], off
	v_lshl_add_u64 v[218:219], s[8:9], 0, v[190:191]
	s_mov_b32 m0, s69
	s_nop 0
	global_load_lds_dwordx4 v[218:219], off
	s_waitcnt vmcnt(8)
	s_waitcnt lgkmcnt(0)
	s_setprio 1
	s_barrier
	v_mfma_f32_16x16x32_bf16 v[152:155], v[98:101], v[164:167], v[152:155]
	v_mfma_f32_16x16x32_bf16 v[140:143], v[122:125], v[164:167], v[140:143]
	v_mfma_f32_16x16x32_bf16 v[118:121], v[98:101], v[172:175], v[118:121]
	v_mfma_f32_16x16x32_bf16 v[114:117], v[122:125], v[172:175], v[114:117]
	v_mfma_f32_16x16x32_bf16 v[94:97], v[98:101], v[180:183], v[94:97]
	v_mfma_f32_16x16x32_bf16 v[90:93], v[122:125], v[180:183], v[90:93]
	v_mfma_f32_16x16x32_bf16 v[78:81], v[98:101], v[198:201], v[78:81]
	v_mfma_f32_16x16x32_bf16 v[74:77], v[122:125], v[198:201], v[74:77]
	v_mfma_f32_16x16x32_bf16 v[152:155], v[102:105], v[168:171], v[152:155]
	v_mfma_f32_16x16x32_bf16 v[140:143], v[126:129], v[168:171], v[140:143]
	v_mfma_f32_16x16x32_bf16 v[118:121], v[102:105], v[176:179], v[118:121]
	v_mfma_f32_16x16x32_bf16 v[114:117], v[126:129], v[176:179], v[114:117]
	v_mfma_f32_16x16x32_bf16 v[94:97], v[102:105], v[184:187], v[94:97]
	v_mfma_f32_16x16x32_bf16 v[90:93], v[126:129], v[184:187], v[90:93]
	v_mfma_f32_16x16x32_bf16 v[78:81], v[102:105], v[202:205], v[78:81]
	v_mfma_f32_16x16x32_bf16 v[74:77], v[126:129], v[202:205], v[74:77]
	v_mfma_f32_16x16x32_bf16 v[136:139], v[144:147], v[164:167], v[136:139]
	v_mfma_f32_16x16x32_bf16 v[132:135], v[156:159], v[164:167], v[132:135]
	v_mfma_f32_16x16x32_bf16 v[110:113], v[144:147], v[172:175], v[110:113]
	v_mfma_f32_16x16x32_bf16 v[106:109], v[156:159], v[172:175], v[106:109]
	v_mfma_f32_16x16x32_bf16 v[86:89], v[144:147], v[180:183], v[86:89]
	v_mfma_f32_16x16x32_bf16 v[82:85], v[156:159], v[180:183], v[82:85]
	v_mfma_f32_16x16x32_bf16 v[70:73], v[144:147], v[198:201], v[70:73]
	v_mfma_f32_16x16x32_bf16 v[66:69], v[156:159], v[198:201], v[66:69]
	v_mfma_f32_16x16x32_bf16 v[136:139], v[148:151], v[168:171], v[136:139]
	v_mfma_f32_16x16x32_bf16 v[132:135], v[160:163], v[168:171], v[132:135]
	v_mfma_f32_16x16x32_bf16 v[110:113], v[148:151], v[176:179], v[110:113]
	v_mfma_f32_16x16x32_bf16 v[106:109], v[160:163], v[176:179], v[106:109]
	v_mfma_f32_16x16x32_bf16 v[86:89], v[148:151], v[184:187], v[86:89]
	v_mfma_f32_16x16x32_bf16 v[82:85], v[160:163], v[184:187], v[82:85]
	v_mfma_f32_16x16x32_bf16 v[70:73], v[148:151], v[202:205], v[70:73]
	v_mfma_f32_16x16x32_bf16 v[66:69], v[160:163], v[202:205], v[66:69]
	s_barrier
	s_setprio 0
	s_add_i32 s8, s10, s64
	v_lshl_add_u64 v[206:207], v[206:207], 0, s[82:83]
	s_mov_b32 m0, s8
	ds_read_b128 v[164:167], v231 offset:49152
	ds_read_b128 v[168:171], v231 offset:50176
	ds_read_b128 v[172:175], v231 offset:51200
	ds_read_b128 v[176:179], v231 offset:52224
	ds_read_b128 v[180:183], v231 offset:53248
	ds_read_b128 v[184:187], v231 offset:54272
	ds_read_b128 v[198:201], v231 offset:55296
	ds_read_b128 v[202:205], v231 offset:56320
	global_load_lds_dwordx4 v[206:207], off
	v_lshl_add_u64 v[206:207], v[208:209], 0, s[82:83]
	s_add_i32 m0, s8, 0x2000
	s_add_i32 s8, s11, s64
	global_load_lds_dwordx4 v[206:207], off
	v_lshl_add_u64 v[206:207], v[210:211], 0, s[82:83]
	s_mov_b32 m0, s8
	s_nop 0
	global_load_lds_dwordx4 v[206:207], off
	v_lshl_add_u64 v[206:207], v[212:213], 0, s[82:83]
	s_add_i32 m0, s8, 0x2000
	s_nop 0
	global_load_lds_dwordx4 v[206:207], off
	v_lshl_add_u64 v[206:207], v[214:215], 0, s[82:83]
	s_mov_b32 m0, s85
	s_nop 0
	global_load_lds_dwordx4 v[206:207], off
	v_lshl_add_u64 v[206:207], v[216:217], 0, s[82:83]
	s_mov_b32 m0, s88
	s_nop 0
	global_load_lds_dwordx4 v[206:207], off
	s_waitcnt vmcnt(8)
	s_waitcnt lgkmcnt(0)
	s_setprio 1
	s_barrier
	v_mfma_f32_16x16x32_bf16 v[62:65], v[98:101], v[164:167], v[62:65]
	v_mfma_f32_16x16x32_bf16 v[58:61], v[122:125], v[164:167], v[58:61]
	v_mfma_f32_16x16x32_bf16 v[46:49], v[98:101], v[172:175], v[46:49]
	v_mfma_f32_16x16x32_bf16 v[42:45], v[122:125], v[172:175], v[42:45]
	v_mfma_f32_16x16x32_bf16 v[30:33], v[98:101], v[180:183], v[30:33]
	v_mfma_f32_16x16x32_bf16 v[26:29], v[122:125], v[180:183], v[26:29]
	v_mfma_f32_16x16x32_bf16 v[14:17], v[98:101], v[198:201], v[14:17]
	v_mfma_f32_16x16x32_bf16 v[10:13], v[122:125], v[198:201], v[10:13]
	v_mfma_f32_16x16x32_bf16 v[62:65], v[102:105], v[168:171], v[62:65]
	v_mfma_f32_16x16x32_bf16 v[58:61], v[126:129], v[168:171], v[58:61]
	v_mfma_f32_16x16x32_bf16 v[46:49], v[102:105], v[176:179], v[46:49]
	v_mfma_f32_16x16x32_bf16 v[42:45], v[126:129], v[176:179], v[42:45]
	v_mfma_f32_16x16x32_bf16 v[30:33], v[102:105], v[184:187], v[30:33]
	v_mfma_f32_16x16x32_bf16 v[26:29], v[126:129], v[184:187], v[26:29]
	v_mfma_f32_16x16x32_bf16 v[14:17], v[102:105], v[202:205], v[14:17]
	v_mfma_f32_16x16x32_bf16 v[10:13], v[126:129], v[202:205], v[10:13]
	v_mfma_f32_16x16x32_bf16 v[54:57], v[144:147], v[164:167], v[54:57]
	v_mfma_f32_16x16x32_bf16 v[50:53], v[156:159], v[164:167], v[50:53]
	v_mfma_f32_16x16x32_bf16 v[38:41], v[144:147], v[172:175], v[38:41]
	v_mfma_f32_16x16x32_bf16 v[34:37], v[156:159], v[172:175], v[34:37]
	v_mfma_f32_16x16x32_bf16 v[22:25], v[144:147], v[180:183], v[22:25]
	v_mfma_f32_16x16x32_bf16 v[18:21], v[156:159], v[180:183], v[18:21]
	v_mfma_f32_16x16x32_bf16 v[6:9], v[144:147], v[198:201], v[6:9]
	v_mfma_f32_16x16x32_bf16 v[2:5], v[156:159], v[198:201], v[2:5]
	v_mfma_f32_16x16x32_bf16 v[54:57], v[148:151], v[168:171], v[54:57]
	v_mfma_f32_16x16x32_bf16 v[50:53], v[160:163], v[168:171], v[50:53]
	v_mfma_f32_16x16x32_bf16 v[38:41], v[148:151], v[176:179], v[38:41]
	v_mfma_f32_16x16x32_bf16 v[34:37], v[160:163], v[176:179], v[34:37]
	v_mfma_f32_16x16x32_bf16 v[22:25], v[148:151], v[184:187], v[22:25]
	v_mfma_f32_16x16x32_bf16 v[18:21], v[160:163], v[184:187], v[18:21]
	v_mfma_f32_16x16x32_bf16 v[6:9], v[148:151], v[202:205], v[6:9]
	v_mfma_f32_16x16x32_bf16 v[2:5], v[160:163], v[202:205], v[2:5]
	s_barrier
	s_setprio 0
	s_add_u32 s60, s60, 0x100
	s_addc_u32 s61, s61, 0
	s_add_u32 s7, s7, 0x100
	s_addc_u32 s40, s40, 0
	s_cmp_ge_u32 s41, s73
	s_mov_b32 s28, s41
	s_cbranch_scc0 .LBB0_75
	s_and_b64 vcc, exec, s[54:55]
	s_cbranch_vccz .LBB0_78
	s_barrier

.LBB0_497:
	s_add_u32 s8, s60, 0xfffc0080
	s_addc_u32 s9, s61, -1
	s_add_i32 s10, 0, 0x10000
	s_cmp_eq_u32 s84, 12
	s_cselect_b32 s41, s55, s9
	s_cselect_b32 s40, s72, s8
	s_cselect_b32 s29, s53, s77
	s_cselect_b32 s28, s73, s76
	s_add_i32 s11, 0, 0x14000
	v_add_u32_e32 v158, s10, v1
	v_add_u32_e32 v174, s11, v1
	ds_read_b128 v[146:149], v158
	ds_read_b128 v[150:153], v158 offset:1024
	ds_read_b128 v[154:157], v158 offset:2048
	ds_read_b128 v[158:161], v158 offset:3072
	ds_read_b128 v[162:165], v174
	ds_read_b128 v[166:169], v174 offset:1024
	ds_read_b128 v[170:173], v174 offset:2048
	ds_read_b128 v[174:177], v174 offset:3072
	v_lshl_add_u64 v[210:211], s[60:61], 0, v[138:139]
	s_add_i32 m0, s62, 0xc000
	ds_read_b128 v[178:181], v145
	ds_read_b128 v[182:185], v145 offset:1024
	ds_read_b128 v[186:189], v145 offset:2048
	ds_read_b128 v[190:193], v145 offset:3072
	ds_read_b128 v[194:197], v145 offset:4096
	ds_read_b128 v[198:201], v145 offset:5120
	ds_read_b128 v[202:205], v145 offset:6144
	ds_read_b128 v[206:209], v145 offset:7168
	global_load_lds_dwordx4 v[210:211], off
	v_lshl_add_u64 v[210:211], s[60:61], 0, v[140:141]
	s_add_i32 m0, s62, 0xe000
	s_nop 0
	global_load_lds_dwordx4 v[210:211], off
	s_waitcnt vmcnt(8)
	s_waitcnt lgkmcnt(0)
	s_setprio 1
	s_barrier
	v_mfma_f32_16x16x32_bf16 v[126:129], v[146:149], v[178:181], v[126:129]
	v_mfma_f32_16x16x32_bf16 v[122:125], v[154:157], v[178:181], v[122:125]
	v_mfma_f32_16x16x32_bf16 v[110:113], v[146:149], v[186:189], v[110:113]
	v_mfma_f32_16x16x32_bf16 v[106:109], v[154:157], v[186:189], v[106:109]
	v_mfma_f32_16x16x32_bf16 v[94:97], v[146:149], v[194:197], v[94:97]
	v_mfma_f32_16x16x32_bf16 v[90:93], v[154:157], v[194:197], v[90:93]
	v_mfma_f32_16x16x32_bf16 v[78:81], v[146:149], v[202:205], v[78:81]
	v_mfma_f32_16x16x32_bf16 v[74:77], v[154:157], v[202:205], v[74:77]
	v_mfma_f32_16x16x32_bf16 v[126:129], v[150:153], v[182:185], v[126:129]
	v_mfma_f32_16x16x32_bf16 v[122:125], v[158:161], v[182:185], v[122:125]
	v_mfma_f32_16x16x32_bf16 v[110:113], v[150:153], v[190:193], v[110:113]
	v_mfma_f32_16x16x32_bf16 v[106:109], v[158:161], v[190:193], v[106:109]
	v_mfma_f32_16x16x32_bf16 v[94:97], v[150:153], v[198:201], v[94:97]
	v_mfma_f32_16x16x32_bf16 v[90:93], v[158:161], v[198:201], v[90:93]
	v_mfma_f32_16x16x32_bf16 v[78:81], v[150:153], v[206:209], v[78:81]
	v_mfma_f32_16x16x32_bf16 v[74:77], v[158:161], v[206:209], v[74:77]
	v_mfma_f32_16x16x32_bf16 v[118:121], v[162:165], v[178:181], v[118:121]
	v_mfma_f32_16x16x32_bf16 v[114:117], v[170:173], v[178:181], v[114:117]
	v_mfma_f32_16x16x32_bf16 v[102:105], v[162:165], v[186:189], v[102:105]
	v_mfma_f32_16x16x32_bf16 v[98:101], v[170:173], v[186:189], v[98:101]
	v_mfma_f32_16x16x32_bf16 v[86:89], v[162:165], v[194:197], v[86:89]
	v_mfma_f32_16x16x32_bf16 v[82:85], v[170:173], v[194:197], v[82:85]
	v_mfma_f32_16x16x32_bf16 v[70:73], v[162:165], v[202:205], v[70:73]
	v_mfma_f32_16x16x32_bf16 v[66:69], v[170:173], v[202:205], v[66:69]
	v_mfma_f32_16x16x32_bf16 v[118:121], v[166:169], v[182:185], v[118:121]
	v_mfma_f32_16x16x32_bf16 v[114:117], v[174:177], v[182:185], v[114:117]
	v_mfma_f32_16x16x32_bf16 v[102:105], v[166:169], v[190:193], v[102:105]
	v_mfma_f32_16x16x32_bf16 v[98:101], v[174:177], v[190:193], v[98:101]
	v_mfma_f32_16x16x32_bf16 v[86:89], v[166:169], v[198:201], v[86:89]
	v_mfma_f32_16x16x32_bf16 v[82:85], v[174:177], v[198:201], v[82:85]
	v_mfma_f32_16x16x32_bf16 v[70:73], v[166:169], v[206:209], v[70:73]
	v_mfma_f32_16x16x32_bf16 v[66:69], v[174:177], v[206:209], v[66:69]
	s_barrier
	s_setprio 0
	s_add_i32 s8, s10, s34
	v_lshl_add_u64 v[210:211], s[28:29], 0, v[130:131]
	s_mov_b32 m0, s8
	ds_read_b128 v[178:181], v145 offset:16384
	ds_read_b128 v[182:185], v145 offset:17408
	ds_read_b128 v[186:189], v145 offset:18432
	ds_read_b128 v[190:193], v145 offset:19456
	ds_read_b128 v[194:197], v145 offset:20480
	ds_read_b128 v[198:201], v145 offset:21504
	ds_read_b128 v[202:205], v145 offset:22528
	ds_read_b128 v[206:209], v145 offset:23552
	global_load_lds_dwordx4 v[210:211], off
	s_add_i32 m0, s8, 0x2000
	s_add_u32 s8, s28, 0x40000
	v_lshl_add_u64 v[212:213], s[28:29], 0, v[132:133]
	s_addc_u32 s9, s29, 0
	s_add_i32 s10, s11, s34
	global_load_lds_dwordx4 v[212:213], off
	v_lshl_add_u64 v[214:215], s[8:9], 0, v[130:131]
	s_mov_b32 m0, s10
	v_lshl_add_u64 v[216:217], s[40:41], 0, v[134:135]
	global_load_lds_dwordx4 v[214:215], off
	v_lshl_add_u64 v[214:215], s[8:9], 0, v[132:133]
	s_add_i32 m0, s10, 0x2000
	s_nop 0
	global_load_lds_dwordx4 v[214:215], off
	v_lshl_add_u64 v[214:215], s[40:41], 0, v[136:137]
	s_mov_b32 m0, s62
	s_nop 0
	global_load_lds_dwordx4 v[214:215], off
	s_mov_b32 m0, s63
	s_nop 0
	global_load_lds_dwordx4 v[216:217], off
	s_waitcnt vmcnt(8)
	s_waitcnt lgkmcnt(0)
	s_setprio 1
	s_barrier
	v_mfma_f32_16x16x32_bf16 v[62:65], v[146:149], v[178:181], v[62:65]
	v_mfma_f32_16x16x32_bf16 v[58:61], v[154:157], v[178:181], v[58:61]
	v_mfma_f32_16x16x32_bf16 v[46:49], v[146:149], v[186:189], v[46:49]
	v_mfma_f32_16x16x32_bf16 v[42:45], v[154:157], v[186:189], v[42:45]
	v_mfma_f32_16x16x32_bf16 v[30:33], v[146:149], v[194:197], v[30:33]
	v_mfma_f32_16x16x32_bf16 v[26:29], v[154:157], v[194:197], v[26:29]
	v_mfma_f32_16x16x32_bf16 v[14:17], v[146:149], v[202:205], v[14:17]
	v_mfma_f32_16x16x32_bf16 v[10:13], v[154:157], v[202:205], v[10:13]
	v_mfma_f32_16x16x32_bf16 v[62:65], v[150:153], v[182:185], v[62:65]
	v_mfma_f32_16x16x32_bf16 v[58:61], v[158:161], v[182:185], v[58:61]
	v_mfma_f32_16x16x32_bf16 v[46:49], v[150:153], v[190:193], v[46:49]
	v_mfma_f32_16x16x32_bf16 v[42:45], v[158:161], v[190:193], v[42:45]
	v_mfma_f32_16x16x32_bf16 v[30:33], v[150:153], v[198:201], v[30:33]
	v_mfma_f32_16x16x32_bf16 v[26:29], v[158:161], v[198:201], v[26:29]
	v_mfma_f32_16x16x32_bf16 v[14:17], v[150:153], v[206:209], v[14:17]
	v_mfma_f32_16x16x32_bf16 v[10:13], v[158:161], v[206:209], v[10:13]
	v_mfma_f32_16x16x32_bf16 v[54:57], v[162:165], v[178:181], v[54:57]
	v_mfma_f32_16x16x32_bf16 v[50:53], v[170:173], v[178:181], v[50:53]
	v_mfma_f32_16x16x32_bf16 v[38:41], v[162:165], v[186:189], v[38:41]
	v_mfma_f32_16x16x32_bf16 v[34:37], v[170:173], v[186:189], v[34:37]
	v_mfma_f32_16x16x32_bf16 v[22:25], v[162:165], v[194:197], v[22:25]
	v_mfma_f32_16x16x32_bf16 v[18:21], v[170:173], v[194:197], v[18:21]
	v_mfma_f32_16x16x32_bf16 v[6:9], v[162:165], v[202:205], v[6:9]
	v_mfma_f32_16x16x32_bf16 v[2:5], v[170:173], v[202:205], v[2:5]
	v_mfma_f32_16x16x32_bf16 v[54:57], v[166:169], v[182:185], v[54:57]
	v_mfma_f32_16x16x32_bf16 v[50:53], v[174:177], v[182:185], v[50:53]
	v_mfma_f32_16x16x32_bf16 v[38:41], v[166:169], v[190:193], v[38:41]
	v_mfma_f32_16x16x32_bf16 v[34:37], v[174:177], v[190:193], v[34:37]
	v_mfma_f32_16x16x32_bf16 v[22:25], v[166:169], v[198:201], v[22:25]
	v_mfma_f32_16x16x32_bf16 v[18:21], v[174:177], v[198:201], v[18:21]
	v_mfma_f32_16x16x32_bf16 v[6:9], v[166:169], v[206:209], v[6:9]
	v_mfma_f32_16x16x32_bf16 v[2:5], v[174:177], v[206:209], v[2:5]
	s_barrier
	s_setprio 0
	s_add_i32 s10, 0, 0x18000
	s_add_i32 s11, 0, 0x1c000
	v_add_u32_e32 v158, s10, v1
	v_add_u32_e32 v174, s11, v1
	ds_read_b128 v[146:149], v158
	ds_read_b128 v[150:153], v158 offset:1024
	ds_read_b128 v[154:157], v158 offset:2048
	ds_read_b128 v[158:161], v158 offset:3072
	ds_read_b128 v[162:165], v174
	ds_read_b128 v[166:169], v174 offset:1024
	ds_read_b128 v[170:173], v174 offset:2048
	ds_read_b128 v[174:177], v174 offset:3072
	s_add_u32 s8, s40, 0x40000
	s_addc_u32 s9, s41, 0
	s_mov_b32 m0, s64
	v_lshl_add_u64 v[218:219], s[8:9], 0, v[136:137]
	ds_read_b128 v[178:181], v145 offset:32768
	ds_read_b128 v[182:185], v145 offset:33792
	ds_read_b128 v[186:189], v145 offset:34816
	ds_read_b128 v[190:193], v145 offset:35840
	ds_read_b128 v[194:197], v145 offset:36864
	ds_read_b128 v[198:201], v145 offset:37888
	ds_read_b128 v[202:205], v145 offset:38912
	ds_read_b128 v[206:209], v145 offset:39936
	global_load_lds_dwordx4 v[218:219], off
	v_lshl_add_u64 v[218:219], s[8:9], 0, v[134:135]
	s_mov_b32 m0, s65
	s_nop 0
	global_load_lds_dwordx4 v[218:219], off
	s_waitcnt vmcnt(8)
	s_waitcnt lgkmcnt(0)
	s_setprio 1
	s_barrier
	v_mfma_f32_16x16x32_bf16 v[126:129], v[146:149], v[178:181], v[126:129]
	v_mfma_f32_16x16x32_bf16 v[122:125], v[154:157], v[178:181], v[122:125]
	v_mfma_f32_16x16x32_bf16 v[110:113], v[146:149], v[186:189], v[110:113]
	v_mfma_f32_16x16x32_bf16 v[106:109], v[154:157], v[186:189], v[106:109]
	v_mfma_f32_16x16x32_bf16 v[94:97], v[146:149], v[194:197], v[94:97]
	v_mfma_f32_16x16x32_bf16 v[90:93], v[154:157], v[194:197], v[90:93]
	v_mfma_f32_16x16x32_bf16 v[78:81], v[146:149], v[202:205], v[78:81]
	v_mfma_f32_16x16x32_bf16 v[74:77], v[154:157], v[202:205], v[74:77]
	v_mfma_f32_16x16x32_bf16 v[126:129], v[150:153], v[182:185], v[126:129]
	v_mfma_f32_16x16x32_bf16 v[122:125], v[158:161], v[182:185], v[122:125]
	v_mfma_f32_16x16x32_bf16 v[110:113], v[150:153], v[190:193], v[110:113]
	v_mfma_f32_16x16x32_bf16 v[106:109], v[158:161], v[190:193], v[106:109]
	v_mfma_f32_16x16x32_bf16 v[94:97], v[150:153], v[198:201], v[94:97]
	v_mfma_f32_16x16x32_bf16 v[90:93], v[158:161], v[198:201], v[90:93]
	v_mfma_f32_16x16x32_bf16 v[78:81], v[150:153], v[206:209], v[78:81]
	v_mfma_f32_16x16x32_bf16 v[74:77], v[158:161], v[206:209], v[74:77]
	v_mfma_f32_16x16x32_bf16 v[118:121], v[162:165], v[178:181], v[118:121]
	v_mfma_f32_16x16x32_bf16 v[114:117], v[170:173], v[178:181], v[114:117]
	v_mfma_f32_16x16x32_bf16 v[102:105], v[162:165], v[186:189], v[102:105]
	v_mfma_f32_16x16x32_bf16 v[98:101], v[170:173], v[186:189], v[98:101]
	v_mfma_f32_16x16x32_bf16 v[86:89], v[162:165], v[194:197], v[86:89]
	v_mfma_f32_16x16x32_bf16 v[82:85], v[170:173], v[194:197], v[82:85]
	v_mfma_f32_16x16x32_bf16 v[70:73], v[162:165], v[202:205], v[70:73]
	v_mfma_f32_16x16x32_bf16 v[66:69], v[170:173], v[202:205], v[66:69]
	v_mfma_f32_16x16x32_bf16 v[118:121], v[166:169], v[182:185], v[118:121]
	v_mfma_f32_16x16x32_bf16 v[114:117], v[174:177], v[182:185], v[114:117]
	v_mfma_f32_16x16x32_bf16 v[102:105], v[166:169], v[190:193], v[102:105]
	v_mfma_f32_16x16x32_bf16 v[98:101], v[174:177], v[190:193], v[98:101]
	v_mfma_f32_16x16x32_bf16 v[86:89], v[166:169], v[198:201], v[86:89]
	v_mfma_f32_16x16x32_bf16 v[82:85], v[174:177], v[198:201], v[82:85]
	v_mfma_f32_16x16x32_bf16 v[70:73], v[166:169], v[206:209], v[70:73]
	v_mfma_f32_16x16x32_bf16 v[66:69], v[174:177], v[206:209], v[66:69]
	s_barrier
	s_setprio 0
	s_add_i32 s8, s10, s34
	v_lshl_add_u64 v[210:211], v[210:211], 0, s[82:83]
	s_mov_b32 m0, s8
	ds_read_b128 v[178:181], v145 offset:49152
	ds_read_b128 v[182:185], v145 offset:50176
	ds_read_b128 v[186:189], v145 offset:51200
	ds_read_b128 v[190:193], v145 offset:52224
	ds_read_b128 v[194:197], v145 offset:53248
	ds_read_b128 v[198:201], v145 offset:54272
	ds_read_b128 v[202:205], v145 offset:55296
	ds_read_b128 v[206:209], v145 offset:56320
	global_load_lds_dwordx4 v[210:211], off
	s_add_i32 m0, s8, 0x2000
	s_add_u32 s8, s28, 0x40080
	v_lshl_add_u64 v[210:211], v[212:213], 0, s[82:83]
	s_addc_u32 s9, s29, 0
	s_add_i32 s10, s11, s34
	global_load_lds_dwordx4 v[210:211], off
	v_lshl_add_u64 v[210:211], s[8:9], 0, v[130:131]
	s_mov_b32 m0, s10
	s_nop 0
	global_load_lds_dwordx4 v[210:211], off
	v_lshl_add_u64 v[210:211], s[8:9], 0, v[132:133]
	s_add_i32 m0, s10, 0x2000
	s_nop 0
	global_load_lds_dwordx4 v[210:211], off
	v_lshl_add_u64 v[210:211], v[214:215], 0, s[82:83]
	s_mov_b32 m0, s66
	s_nop 0
	global_load_lds_dwordx4 v[210:211], off
	v_lshl_add_u64 v[210:211], v[216:217], 0, s[82:83]
	s_mov_b32 m0, s67
	s_nop 0
	global_load_lds_dwordx4 v[210:211], off
	s_waitcnt vmcnt(8)
	s_waitcnt lgkmcnt(0)
	s_setprio 1
	s_barrier
	v_mfma_f32_16x16x32_bf16 v[62:65], v[146:149], v[178:181], v[62:65]
	v_mfma_f32_16x16x32_bf16 v[58:61], v[154:157], v[178:181], v[58:61]
	v_mfma_f32_16x16x32_bf16 v[46:49], v[146:149], v[186:189], v[46:49]
	v_mfma_f32_16x16x32_bf16 v[42:45], v[154:157], v[186:189], v[42:45]
	v_mfma_f32_16x16x32_bf16 v[30:33], v[146:149], v[194:197], v[30:33]
	v_mfma_f32_16x16x32_bf16 v[26:29], v[154:157], v[194:197], v[26:29]
	v_mfma_f32_16x16x32_bf16 v[14:17], v[146:149], v[202:205], v[14:17]
	v_mfma_f32_16x16x32_bf16 v[10:13], v[154:157], v[202:205], v[10:13]
	v_mfma_f32_16x16x32_bf16 v[62:65], v[150:153], v[182:185], v[62:65]
	v_mfma_f32_16x16x32_bf16 v[58:61], v[158:161], v[182:185], v[58:61]
	v_mfma_f32_16x16x32_bf16 v[46:49], v[150:153], v[190:193], v[46:49]
	v_mfma_f32_16x16x32_bf16 v[42:45], v[158:161], v[190:193], v[42:45]
	v_mfma_f32_16x16x32_bf16 v[30:33], v[150:153], v[198:201], v[30:33]
	v_mfma_f32_16x16x32_bf16 v[26:29], v[158:161], v[198:201], v[26:29]
	v_mfma_f32_16x16x32_bf16 v[14:17], v[150:153], v[206:209], v[14:17]
	v_mfma_f32_16x16x32_bf16 v[10:13], v[158:161], v[206:209], v[10:13]
	v_mfma_f32_16x16x32_bf16 v[54:57], v[162:165], v[178:181], v[54:57]
	v_mfma_f32_16x16x32_bf16 v[50:53], v[170:173], v[178:181], v[50:53]
	v_mfma_f32_16x16x32_bf16 v[38:41], v[162:165], v[186:189], v[38:41]
	v_mfma_f32_16x16x32_bf16 v[34:37], v[170:173], v[186:189], v[34:37]
	v_mfma_f32_16x16x32_bf16 v[22:25], v[162:165], v[194:197], v[22:25]
	v_mfma_f32_16x16x32_bf16 v[18:21], v[170:173], v[194:197], v[18:21]
	v_mfma_f32_16x16x32_bf16 v[6:9], v[162:165], v[202:205], v[6:9]
	v_mfma_f32_16x16x32_bf16 v[2:5], v[170:173], v[202:205], v[2:5]
	v_mfma_f32_16x16x32_bf16 v[54:57], v[166:169], v[182:185], v[54:57]
	v_mfma_f32_16x16x32_bf16 v[50:53], v[174:177], v[182:185], v[50:53]
	v_mfma_f32_16x16x32_bf16 v[38:41], v[166:169], v[190:193], v[38:41]
	v_mfma_f32_16x16x32_bf16 v[34:37], v[174:177], v[190:193], v[34:37]
	v_mfma_f32_16x16x32_bf16 v[22:25], v[166:169], v[198:201], v[22:25]
	v_mfma_f32_16x16x32_bf16 v[18:21], v[174:177], v[198:201], v[18:21]
	v_mfma_f32_16x16x32_bf16 v[6:9], v[166:169], v[206:209], v[6:9]
	v_mfma_f32_16x16x32_bf16 v[2:5], v[174:177], v[206:209], v[2:5]
	s_barrier
	s_setprio 0
	s_add_i32 s84, s84, 2
	s_add_u32 s60, s60, 0x100
	s_addc_u32 s61, s61, 0
	s_add_u32 s76, s76, 0x100
	s_addc_u32 s77, s77, 0
	s_cmp_gt_u32 s84, 13
	s_cbranch_scc0 .LBB0_497
	s_and_b64 vcc, exec, s[50:51]
	s_cbranch_vccz .LBB0_500
	s_barrier
